# step barrier: s_sleep removed from the workgroups' release-poll loop (poll period bounded by the load round trip only)
# baseline (speedup 1.0000x reference)
; __device__ __forceinline__ unsigned xb_ld(unsigned* p)              { return __hip_atomic_load(p, __ATOMIC_RELAXED, __HIP_MEMORY_SCOPE_AGENT); }
; #define XB_SPIN(cond, bar) do { unsigned _sp = 0; while (cond) { __builtin_amdgcn_s_sleep(1); \
;     if ((++_sp & 255u) == 0u) { if (xb_ld(&(bar)[XB_TMO])) break; if (_sp > XB_SPIN_CAP) { atomicAdd(&(bar)[XB_TMO], 1u); break; } } } } while (0)
; __device__ __forceinline__ void xcd_barrier(const XcdBarrier& b) {
;     ...
;         } else {
;             XB_SPIN(xb_ld(&bar[XB_XGEN(b.x)]) == gen, bar);
;             __builtin_amdgcn_fence(__ATOMIC_ACQUIRE, "agent");
;             asm volatile("s_waitcnt vmcnt(0)" ::: "memory");
.LBB0_818:
	s_and_b32 s16, s24, 0xff
	s_mov_b64 s[14:15], -1
	s_cmp_lg_u32 s16, 0
	s_mov_b64 s[16:17], -1
	s_cbranch_scc1 .LBB0_822
	v_mov_b64_e32 v[2:3], s[36:37]
	flat_load_dword v2, v[2:3] offset:512 sc1
	s_mov_b64 s[16:17], 0
	s_mov_b64 s[18:19], -1
	s_waitcnt vmcnt(0) lgkmcnt(0)
	v_cmp_eq_u32_e32 vcc, 0, v2
	s_and_saveexec_b64 s[20:21], vcc
	s_cmp_lt_u32 s24, 0x40001
	s_cselect_b64 s[16:17], -1, 0
	s_xor_b64 s[18:19], exec, -1
	s_and_b64 s[16:17], s[16:17], exec
	s_or_b64 exec, exec, s[20:21]
